# G1-odd cos/sin column pass: in-wave LDS transpose so U^T stores write whole 128B lines
# speedup vs baseline: 1.0435x; 1.0407x over previous
.LBB0_168:
	s_andn2_b64 vcc, exec, s[0:1]
	s_mov_b32 s96, 0x800000
	s_cbranch_vccnz .LBB0_150
	s_lshl_b32 s0, s41, 8
	s_lshl_b32 s1, s54, 8
	s_and_b32 s0, s0, 0x400
	s_and_b32 s2, s1, 0x300
	s_or_b32 s0, s0, s2
	s_mulk_i32 s0, 0x5080
	s_add_u32 s0, s10, s0
	s_addc_u32 s1, s11, 0
	s_lshl_b32 s24, s55, 1
	s_add_u32 s0, s0, s24
	s_addc_u32 s1, s1, 0
	s_mov_b64 s[20:21], exec
	v_readlane_b32 s22, v246, 22
	v_readlane_b32 s23, v246, 23
	s_and_b64 s[22:23], s[20:21], s[22:23]
	s_xor_b64 s[20:21], s[22:23], s[20:21]
	s_mov_b64 exec, s[22:23]
	s_cbranch_execz .LBB0_171
	s_mov_b64 s[34:35], exec
	s_mov_b64 exec, -1
	v_lshl_add_u64 v[104:105], s[0:1], 0, v[146:147]
	v_mov_b32_e32 v137, v147
	s_cmp_lt_u32 s41, 4
	v_lshl_add_u64 v[106:107], s[0:1], 0, v[136:137]
	s_cselect_b32 s22, 0, 0x80008000
	v_lshlrev_b64 v[108:109], 1, v[132:133]
	v_lshl_add_u64 v[100:101], v[104:105], 0, v[108:109]
	v_lshl_add_u64 v[102:103], v[106:107], 0, v[108:109]
	v_lshrrev_b32_e32 v110, 7, v0
	v_and_b32_e32 v111, 0x7f, v0
	s_mov_b32 s44, 0x8400
	v_mul_lo_u32 v112, v110, s44
	v_lshl_add_u32 v113, v111, 2, v112
	v_lshlrev_b32_e32 v114, 8, v110
	v_add_u32_e32 v114, 0x10800, v114
	v_lshlrev_b32_e32 v115, 2, v111
	v_add_u32_e32 v115, 0x10a00, v115
	ds_read_b32 v2, v115
	ds_read_b32 v36, v113 offset:0
	ds_read_b32 v37, v113 offset:528
	ds_read_b32 v38, v113 offset:1056
	ds_read_b32 v39, v113 offset:1584
	ds_read_b32 v40, v113 offset:2112
	ds_read_b32 v41, v113 offset:2640
	ds_read_b32 v42, v113 offset:3168
	ds_read_b32 v43, v113 offset:3696
	ds_read_b128 v[68:71], v114 offset:0
	ds_read_b128 v[72:75], v114 offset:16
	ds_read_b32 v44, v113 offset:4224
	ds_read_b32 v45, v113 offset:4752
	ds_read_b32 v46, v113 offset:5280
	ds_read_b32 v47, v113 offset:5808
	ds_read_b32 v48, v113 offset:6336
	ds_read_b32 v49, v113 offset:6864
	ds_read_b32 v50, v113 offset:7392
	ds_read_b32 v51, v113 offset:7920
	ds_read_b128 v[76:79], v114 offset:32
	ds_read_b128 v[80:83], v114 offset:48
	ds_read_b32 v52, v113 offset:8448
	ds_read_b32 v53, v113 offset:8976
	ds_read_b32 v54, v113 offset:9504
	ds_read_b32 v55, v113 offset:10032
	ds_read_b32 v56, v113 offset:10560
	ds_read_b32 v57, v113 offset:11088
	ds_read_b32 v58, v113 offset:11616
	ds_read_b32 v59, v113 offset:12144
	ds_read_b128 v[84:87], v114 offset:64
	ds_read_b128 v[88:91], v114 offset:80
	ds_read_b32 v60, v113 offset:12672
	ds_read_b32 v61, v113 offset:13200
	ds_read_b32 v62, v113 offset:13728
	ds_read_b32 v63, v113 offset:14256
	ds_read_b32 v64, v113 offset:14784
	ds_read_b32 v65, v113 offset:15312
	ds_read_b32 v66, v113 offset:15840
	ds_read_b32 v67, v113 offset:16368
	ds_read_b128 v[92:95], v114 offset:96
	ds_read_b128 v[96:99], v114 offset:112
	s_waitcnt lgkmcnt(0)
	v_pk_fma_f32 v[36:37], v[36:37], v[68:69], v[2:3] op_sel_hi:[1,1,0]
	v_pk_fma_f32 v[38:39], v[38:39], v[70:71], v[2:3] op_sel_hi:[1,1,0]
	v_pk_fma_f32 v[40:41], v[40:41], v[72:73], v[2:3] op_sel_hi:[1,1,0]
	v_pk_fma_f32 v[42:43], v[42:43], v[74:75], v[2:3] op_sel_hi:[1,1,0]
	v_cvt_pk_bf16_f32 v4, v36, v37
	v_cvt_pk_bf16_f32 v5, v38, v39
	v_cvt_pk_bf16_f32 v6, v40, v41
	v_cvt_pk_bf16_f32 v7, v42, v43
	v_pk_fma_f32 v[44:45], v[44:45], v[76:77], v[2:3] op_sel_hi:[1,1,0]
	v_pk_fma_f32 v[46:47], v[46:47], v[78:79], v[2:3] op_sel_hi:[1,1,0]
	v_pk_fma_f32 v[48:49], v[48:49], v[80:81], v[2:3] op_sel_hi:[1,1,0]
	v_pk_fma_f32 v[50:51], v[50:51], v[82:83], v[2:3] op_sel_hi:[1,1,0]
	v_cvt_pk_bf16_f32 v8, v44, v45
	v_cvt_pk_bf16_f32 v9, v46, v47
	v_cvt_pk_bf16_f32 v10, v48, v49
	v_cvt_pk_bf16_f32 v11, v50, v51
	v_pk_fma_f32 v[52:53], v[52:53], v[84:85], v[2:3] op_sel_hi:[1,1,0]
	v_pk_fma_f32 v[54:55], v[54:55], v[86:87], v[2:3] op_sel_hi:[1,1,0]
	v_pk_fma_f32 v[56:57], v[56:57], v[88:89], v[2:3] op_sel_hi:[1,1,0]
	v_pk_fma_f32 v[58:59], v[58:59], v[90:91], v[2:3] op_sel_hi:[1,1,0]
	v_cvt_pk_bf16_f32 v12, v52, v53
	v_cvt_pk_bf16_f32 v13, v54, v55
	v_cvt_pk_bf16_f32 v14, v56, v57
	v_cvt_pk_bf16_f32 v15, v58, v59
	v_pk_fma_f32 v[60:61], v[60:61], v[92:93], v[2:3] op_sel_hi:[1,1,0]
	v_pk_fma_f32 v[62:63], v[62:63], v[94:95], v[2:3] op_sel_hi:[1,1,0]
	v_pk_fma_f32 v[64:65], v[64:65], v[96:97], v[2:3] op_sel_hi:[1,1,0]
	v_pk_fma_f32 v[66:67], v[66:67], v[98:99], v[2:3] op_sel_hi:[1,1,0]
	v_cvt_pk_bf16_f32 v16, v60, v61
	v_cvt_pk_bf16_f32 v17, v62, v63
	v_cvt_pk_bf16_f32 v18, v64, v65
	v_cvt_pk_bf16_f32 v19, v66, v67
	ds_read_b32 v36, v113 offset:16896
	ds_read_b32 v37, v113 offset:17424
	ds_read_b32 v38, v113 offset:17952
	ds_read_b32 v39, v113 offset:18480
	ds_read_b32 v40, v113 offset:19008
	ds_read_b32 v41, v113 offset:19536
	ds_read_b32 v42, v113 offset:20064
	ds_read_b32 v43, v113 offset:20592
	ds_read_b128 v[68:71], v114 offset:128
	ds_read_b128 v[72:75], v114 offset:144
	ds_read_b32 v44, v113 offset:21120
	ds_read_b32 v45, v113 offset:21648
	ds_read_b32 v46, v113 offset:22176
	ds_read_b32 v47, v113 offset:22704
	ds_read_b32 v48, v113 offset:23232
	ds_read_b32 v49, v113 offset:23760
	ds_read_b32 v50, v113 offset:24288
	ds_read_b32 v51, v113 offset:24816
	ds_read_b128 v[76:79], v114 offset:160
	ds_read_b128 v[80:83], v114 offset:176
	ds_read_b32 v52, v113 offset:25344
	ds_read_b32 v53, v113 offset:25872
	ds_read_b32 v54, v113 offset:26400
	ds_read_b32 v55, v113 offset:26928
	ds_read_b32 v56, v113 offset:27456
	ds_read_b32 v57, v113 offset:27984
	ds_read_b32 v58, v113 offset:28512
	ds_read_b32 v59, v113 offset:29040
	ds_read_b128 v[84:87], v114 offset:192
	ds_read_b128 v[88:91], v114 offset:208
	ds_read_b32 v60, v113 offset:29568
	ds_read_b32 v61, v113 offset:30096
	ds_read_b32 v62, v113 offset:30624
	ds_read_b32 v63, v113 offset:31152
	ds_read_b32 v64, v113 offset:31680
	ds_read_b32 v65, v113 offset:32208
	ds_read_b32 v66, v113 offset:32736
	ds_read_b32 v67, v113 offset:33264
	ds_read_b128 v[92:95], v114 offset:224
	ds_read_b128 v[96:99], v114 offset:240
	s_waitcnt lgkmcnt(0)
	v_pk_fma_f32 v[36:37], v[36:37], v[68:69], v[2:3] op_sel_hi:[1,1,0]
	v_pk_fma_f32 v[38:39], v[38:39], v[70:71], v[2:3] op_sel_hi:[1,1,0]
	v_pk_fma_f32 v[40:41], v[40:41], v[72:73], v[2:3] op_sel_hi:[1,1,0]
	v_pk_fma_f32 v[42:43], v[42:43], v[74:75], v[2:3] op_sel_hi:[1,1,0]
	v_cvt_pk_bf16_f32 v20, v36, v37
	v_cvt_pk_bf16_f32 v21, v38, v39
	v_cvt_pk_bf16_f32 v22, v40, v41
	v_cvt_pk_bf16_f32 v23, v42, v43
	v_pk_fma_f32 v[44:45], v[44:45], v[76:77], v[2:3] op_sel_hi:[1,1,0]
	v_pk_fma_f32 v[46:47], v[46:47], v[78:79], v[2:3] op_sel_hi:[1,1,0]
	v_pk_fma_f32 v[48:49], v[48:49], v[80:81], v[2:3] op_sel_hi:[1,1,0]
	v_pk_fma_f32 v[50:51], v[50:51], v[82:83], v[2:3] op_sel_hi:[1,1,0]
	v_cvt_pk_bf16_f32 v24, v44, v45
	v_cvt_pk_bf16_f32 v25, v46, v47
	v_cvt_pk_bf16_f32 v26, v48, v49
	v_cvt_pk_bf16_f32 v27, v50, v51
	v_pk_fma_f32 v[52:53], v[52:53], v[84:85], v[2:3] op_sel_hi:[1,1,0]
	v_pk_fma_f32 v[54:55], v[54:55], v[86:87], v[2:3] op_sel_hi:[1,1,0]
	v_pk_fma_f32 v[56:57], v[56:57], v[88:89], v[2:3] op_sel_hi:[1,1,0]
	v_pk_fma_f32 v[58:59], v[58:59], v[90:91], v[2:3] op_sel_hi:[1,1,0]
	v_cvt_pk_bf16_f32 v28, v52, v53
	v_cvt_pk_bf16_f32 v29, v54, v55
	v_cvt_pk_bf16_f32 v30, v56, v57
	v_cvt_pk_bf16_f32 v31, v58, v59
	v_pk_fma_f32 v[60:61], v[60:61], v[92:93], v[2:3] op_sel_hi:[1,1,0]
	v_pk_fma_f32 v[62:63], v[62:63], v[94:95], v[2:3] op_sel_hi:[1,1,0]
	v_pk_fma_f32 v[64:65], v[64:65], v[96:97], v[2:3] op_sel_hi:[1,1,0]
	v_pk_fma_f32 v[66:67], v[66:67], v[98:99], v[2:3] op_sel_hi:[1,1,0]
	v_cvt_pk_bf16_f32 v32, v60, v61
	v_cvt_pk_bf16_f32 v33, v62, v63
	v_cvt_pk_bf16_f32 v34, v64, v65
	v_cvt_pk_bf16_f32 v35, v66, v67
	v_and_b32_e32 v116, 63, v0
	v_lshl_add_u32 v117, v110, 6, v116
	v_mul_u32_u24_e32 v117, 0x210, v117
	v_bfe_u32 v118, v0, 6, 1
	v_lshl_add_u32 v117, v118, 8, v117
	v_add_u32_e32 v117, 0x80, v117
	ds_write_b128 v117, v[4:7]
	ds_write_b128 v117, v[8:11] offset:16
	ds_write_b128 v117, v[12:15] offset:32
	ds_write_b128 v117, v[16:19] offset:48
	ds_write_b128 v117, v[20:23] offset:64
	ds_write_b128 v117, v[24:27] offset:80
	ds_write_b128 v117, v[28:31] offset:96
	ds_write_b128 v117, v[32:35] offset:112
	v_lshrrev_b32_e32 v119, 3, v116
	v_lshl_add_u32 v120, v110, 6, v119
	v_mul_u32_u24_e32 v120, 0x210, v120
	v_lshl_add_u32 v120, v118, 8, v120
	v_and_b32_e32 v121, 7, v0
	v_lshl_add_u32 v120, v121, 4, v120
	v_add_u32_e32 v120, 0x80, v120
	v_sub_u32_e32 v122, v119, v116
	v_mul_i32_i24_e32 v122, 0x5080, v122
	v_sub_u32_e32 v124, 0, v122
	v_lshl_add_u32 v122, v121, 4, v122
	v_lshl_add_u32 v124, v121, 4, v124
	v_ashrrev_i32_e32 v123, 31, v122
	v_ashrrev_i32_e32 v125, 31, v124
	v_lshl_add_u64 v[100:101], v[100:101], 0, v[122:123]
	v_lshl_add_u64 v[102:103], v[102:103], 0, v[124:125]
	s_mov_b64 s[44:45], 0x28400
	v_mov_b32_e32 v126, 0x28400
	v_mov_b32_e32 v127, 0
	s_waitcnt lgkmcnt(0)
	ds_read_b128 v[36:39], v120
	ds_read_b128 v[40:43], v120 offset:4224
	ds_read_b128 v[44:47], v120 offset:8448
	ds_read_b128 v[48:51], v120 offset:12672
	ds_read_b128 v[52:55], v120 offset:16896
	ds_read_b128 v[56:59], v120 offset:21120
	ds_read_b128 v[60:63], v120 offset:25344
	ds_read_b128 v[64:67], v120 offset:29568
	s_bitcmp1_b32 s34, 0
	s_cselect_b32 s46, -1, 0xffffff00
	s_mov_b32 s47, -1
	s_mov_b64 exec, s[46:47]
	s_waitcnt lgkmcnt(7)
	global_store_dwordx4 v[100:101], v[36:39], off
	v_xor_b32_e32 v68, s22, v36
	v_xor_b32_e32 v69, s22, v37
	v_xor_b32_e32 v70, s22, v38
	v_xor_b32_e32 v71, s22, v39
	global_store_dwordx4 v[102:103], v[68:71], off
	s_mov_b64 exec, -1
	v_lshl_add_u64 v[100:101], v[100:101], 0, s[44:45]
	v_sub_co_u32_e32 v102, vcc, v102, v126
	s_nop 1
	v_subb_co_u32_e32 v103, vcc, v103, v127, vcc
	s_waitcnt lgkmcnt(6)
	global_store_dwordx4 v[100:101], v[40:43], off
	v_xor_b32_e32 v72, s22, v40
	v_xor_b32_e32 v73, s22, v41
	v_xor_b32_e32 v74, s22, v42
	v_xor_b32_e32 v75, s22, v43
	global_store_dwordx4 v[102:103], v[72:75], off
	v_lshl_add_u64 v[100:101], v[100:101], 0, s[44:45]
	v_sub_co_u32_e32 v102, vcc, v102, v126
	s_nop 1
	v_subb_co_u32_e32 v103, vcc, v103, v127, vcc
	s_waitcnt lgkmcnt(5)
	global_store_dwordx4 v[100:101], v[44:47], off
	v_xor_b32_e32 v76, s22, v44
	v_xor_b32_e32 v77, s22, v45
	v_xor_b32_e32 v78, s22, v46
	v_xor_b32_e32 v79, s22, v47
	global_store_dwordx4 v[102:103], v[76:79], off
	v_lshl_add_u64 v[100:101], v[100:101], 0, s[44:45]
	v_sub_co_u32_e32 v102, vcc, v102, v126
	s_nop 1
	v_subb_co_u32_e32 v103, vcc, v103, v127, vcc
	s_waitcnt lgkmcnt(4)
	global_store_dwordx4 v[100:101], v[48:51], off
	v_xor_b32_e32 v80, s22, v48
	v_xor_b32_e32 v81, s22, v49
	v_xor_b32_e32 v82, s22, v50
	v_xor_b32_e32 v83, s22, v51
	global_store_dwordx4 v[102:103], v[80:83], off
	v_lshl_add_u64 v[100:101], v[100:101], 0, s[44:45]
	v_sub_co_u32_e32 v102, vcc, v102, v126
	s_nop 1
	v_subb_co_u32_e32 v103, vcc, v103, v127, vcc
	s_waitcnt lgkmcnt(3)
	global_store_dwordx4 v[100:101], v[52:55], off
	v_xor_b32_e32 v84, s22, v52
	v_xor_b32_e32 v85, s22, v53
	v_xor_b32_e32 v86, s22, v54
	v_xor_b32_e32 v87, s22, v55
	global_store_dwordx4 v[102:103], v[84:87], off
	v_lshl_add_u64 v[100:101], v[100:101], 0, s[44:45]
	v_sub_co_u32_e32 v102, vcc, v102, v126
	s_nop 1
	v_subb_co_u32_e32 v103, vcc, v103, v127, vcc
	s_waitcnt lgkmcnt(2)
	global_store_dwordx4 v[100:101], v[56:59], off
	v_xor_b32_e32 v88, s22, v56
	v_xor_b32_e32 v89, s22, v57
	v_xor_b32_e32 v90, s22, v58
	v_xor_b32_e32 v91, s22, v59
	global_store_dwordx4 v[102:103], v[88:91], off
	v_lshl_add_u64 v[100:101], v[100:101], 0, s[44:45]
	v_sub_co_u32_e32 v102, vcc, v102, v126
	s_nop 1
	v_subb_co_u32_e32 v103, vcc, v103, v127, vcc
	s_waitcnt lgkmcnt(1)
	global_store_dwordx4 v[100:101], v[60:63], off
	v_xor_b32_e32 v92, s22, v60
	v_xor_b32_e32 v93, s22, v61
	v_xor_b32_e32 v94, s22, v62
	v_xor_b32_e32 v95, s22, v63
	global_store_dwordx4 v[102:103], v[92:95], off
	v_lshl_add_u64 v[100:101], v[100:101], 0, s[44:45]
	v_sub_co_u32_e32 v102, vcc, v102, v126
	s_nop 1
	v_subb_co_u32_e32 v103, vcc, v103, v127, vcc
	s_waitcnt lgkmcnt(0)
	global_store_dwordx4 v[100:101], v[64:67], off
	v_xor_b32_e32 v96, s22, v64
	v_xor_b32_e32 v97, s22, v65
	v_xor_b32_e32 v98, s22, v66
	v_xor_b32_e32 v99, s22, v67
	global_store_dwordx4 v[102:103], v[96:99], off
	s_mov_b64 exec, s[34:35]
